# relu^2 GEMM epilogues (PH8/PH18): canonicalising v_max folded into the relu (214 VALU instructions fewer; s_nop kept where a wide store's data registers are rewritten)
# baseline (speedup 1.0000x reference)
; __device__ __forceinline__ unsigned cvt_pk_bf16(float lo, float hi) { unsigned r; asm volatile("v_cvt_pk_bf16_f32 %0, %1, %2" : "=v"(r) : "v"(lo), "v"(hi)); return r; }
;     __device__ __forceinline__ void operator()(const pg8::f32x4 (&acc)[2][2][4][2], const pg8::Unit& u, int wr, int wc, int fr, int fq) const {
;         const int row0 = u.pm * 256 + wr * 64 + fr, col0 = u.pn * 256 + wc * 32 + 8 * fq;
; #pragma unroll
;         for (int ai = 0; ai < 2; ++ai)
; #pragma unroll
;             for (int m = 0; m < 4; ++m) { bf16* rowp = O + (size_t)(row0 + ai * 128 + m * 16) * ldc + col0;
; #pragma unroll
;                 for (int bj = 0; bj < 2; ++bj) { pg8::f32x4 v0 = acc[ai][bj][m][0], v1 = acc[ai][bj][m][1];
;                     if (ACT == 1) {
; #pragma unroll
;                         for (int e = 0; e < 4; ++e) { float a = fmaxf(v0[e], 0.f), b = fmaxf(v1[e], 0.f); v0[e] = a * a; v1[e] = b * b; } }
;                     u32x4 w; w.x = pg8::cvt_pk_bf16(v0[0], v0[1]); w.y = pg8::cvt_pk_bf16(v0[2], v0[3]); w.z = pg8::cvt_pk_bf16(v1[0], v1[1]); w.w = pg8::cvt_pk_bf16(v1[2], v1[3]);
;                     *(u32x4*)(rowp + bj * 128) = w; } }
.LBB0_871:
	v_lshl_add_u32 v152, s58, 8, v146
	v_ashrrev_i32_e32 v153, 31, v152
	v_max_f32_e32 v120, 0, v120
	v_lshl_or_b32 v144, s85, 8, v148
	v_lshlrev_b64 v[154:155], 14, v[152:153]
	v_mul_f32_e32 v153, v120, v120
	v_max_f32_e32 v121, 0, v121
	v_max_f32_e32 v122, 0, v122
	v_ashrrev_i32_e32 v145, 31, v144
	v_max_f32_e32 v120, 0, v125
	v_mul_f32_e32 v125, v121, v121
	v_max_f32_e32 v121, v126, v126
	v_mul_f32_e32 v126, v122, v122
	v_lshl_add_u64 v[154:155], s[8:9], 0, v[154:155]
	v_lshlrev_b64 v[156:157], 1, v[144:145]
	v_max_f32_e32 v124, 0, v124
	v_mul_f32_e32 v120, v120, v120
	v_max_f32_e32 v121, 0, v121
	v_max_f32_e32 v122, 0, v127
	v_max_f32_e32 v123, 0, v123
	v_lshl_add_u64 v[144:145], v[154:155], 0, v[156:157]
	v_mul_f32_e32 v124, v124, v124
	v_mul_f32_e32 v121, v121, v121
	v_mul_f32_e32 v122, v122, v122
	v_mul_f32_e32 v123, v123, v123
	v_cvt_pk_bf16_f32 v120, v124, v120
	v_max_f32_e32 v112, 0, v112
	v_cvt_pk_bf16_f32 v121, v121, v122
	v_cvt_pk_bf16_f32 v122, v153, v125
	v_cvt_pk_bf16_f32 v123, v126, v123
	global_store_dwordx4 v[144:145], v[120:123], off
	v_max_f32_e32 v113, 0, v113
	v_max_f32_e32 v114, 0, v114
	v_mul_f32_e32 v120, v112, v112
	s_nop 0
	v_max_f32_e32 v112, 0, v117
	v_mul_f32_e32 v117, v113, v113
	v_max_f32_e32 v113, v118, v118
	v_mul_f32_e32 v118, v114, v114
	v_max_f32_e32 v116, 0, v116
	v_mul_f32_e32 v112, v112, v112
	v_max_f32_e32 v113, 0, v113
	v_max_f32_e32 v114, 0, v119
	v_max_f32_e32 v115, 0, v115
	v_mul_f32_e32 v116, v116, v116
	v_mul_f32_e32 v113, v113, v113
	v_mul_f32_e32 v114, v114, v114
	v_mul_f32_e32 v115, v115, v115
	v_cvt_pk_bf16_f32 v112, v116, v112
	v_cvt_pk_bf16_f32 v113, v113, v114
	v_cvt_pk_bf16_f32 v114, v120, v117
	v_cvt_pk_bf16_f32 v115, v118, v115
	global_store_dwordx4 v[144:145], v[112:115], off offset:256
	v_max_f32_e32 v104, 0, v104
	s_nop 0
	v_or_b32_e32 v112, 16, v152
	s_nop 0
	v_ashrrev_i32_e32 v113, 31, v112
	v_mul_f32_e32 v114, v104, v104
	v_max_f32_e32 v105, 0, v105
	v_max_f32_e32 v106, 0, v106
	v_lshlrev_b64 v[112:113], 14, v[112:113]
	v_max_f32_e32 v104, 0, v109
	v_mul_f32_e32 v109, v105, v105
	v_max_f32_e32 v105, v110, v110
	v_mul_f32_e32 v110, v106, v106
	v_lshl_add_u64 v[112:113], s[8:9], 0, v[112:113]
	v_max_f32_e32 v108, 0, v108
	v_mul_f32_e32 v104, v104, v104
	v_max_f32_e32 v105, 0, v105
	v_max_f32_e32 v106, 0, v111
	v_max_f32_e32 v107, 0, v107
	v_lshl_add_u64 v[112:113], v[112:113], 0, v[156:157]
	v_mul_f32_e32 v108, v108, v108
	v_mul_f32_e32 v105, v105, v105
	v_mul_f32_e32 v106, v106, v106
	v_mul_f32_e32 v107, v107, v107
	v_cvt_pk_bf16_f32 v104, v108, v104
	v_max_f32_e32 v96, 0, v96
	v_cvt_pk_bf16_f32 v105, v105, v106
	v_cvt_pk_bf16_f32 v106, v114, v109
	v_cvt_pk_bf16_f32 v107, v110, v107
	global_store_dwordx4 v[112:113], v[104:107], off
	v_max_f32_e32 v97, 0, v97
	v_max_f32_e32 v98, 0, v98
	v_mul_f32_e32 v104, v96, v96
	s_nop 0
	v_max_f32_e32 v96, 0, v101
	v_mul_f32_e32 v101, v97, v97
	v_max_f32_e32 v97, v102, v102
	v_mul_f32_e32 v102, v98, v98
	v_max_f32_e32 v100, 0, v100
	v_mul_f32_e32 v96, v96, v96
	v_max_f32_e32 v97, 0, v97
	v_max_f32_e32 v98, 0, v103
	v_max_f32_e32 v99, 0, v99
	v_mul_f32_e32 v100, v100, v100
	v_mul_f32_e32 v97, v97, v97
	v_mul_f32_e32 v98, v98, v98
	v_mul_f32_e32 v99, v99, v99
	v_cvt_pk_bf16_f32 v96, v100, v96
	v_cvt_pk_bf16_f32 v97, v97, v98
	v_cvt_pk_bf16_f32 v98, v104, v101
	v_cvt_pk_bf16_f32 v99, v102, v99
	global_store_dwordx4 v[112:113], v[96:99], off offset:256
	v_max_f32_e32 v88, 0, v88
	s_nop 0
	v_or_b32_e32 v96, 32, v152
	s_nop 0
	v_ashrrev_i32_e32 v97, 31, v96
	v_mul_f32_e32 v98, v88, v88
	v_max_f32_e32 v89, 0, v89
	v_max_f32_e32 v90, 0, v90
	v_lshlrev_b64 v[96:97], 14, v[96:97]
	v_max_f32_e32 v88, 0, v93
	v_mul_f32_e32 v93, v89, v89
	v_max_f32_e32 v89, v94, v94
	v_mul_f32_e32 v94, v90, v90
	v_lshl_add_u64 v[96:97], s[8:9], 0, v[96:97]
	v_max_f32_e32 v92, 0, v92
	v_mul_f32_e32 v88, v88, v88
	v_max_f32_e32 v89, 0, v89
	v_max_f32_e32 v90, 0, v95
	v_max_f32_e32 v91, 0, v91
	v_lshl_add_u64 v[96:97], v[96:97], 0, v[156:157]
	v_mul_f32_e32 v92, v92, v92
	v_mul_f32_e32 v89, v89, v89
	v_mul_f32_e32 v90, v90, v90
	v_mul_f32_e32 v91, v91, v91
	v_cvt_pk_bf16_f32 v88, v92, v88
	v_max_f32_e32 v80, 0, v80
	v_cvt_pk_bf16_f32 v89, v89, v90
	v_cvt_pk_bf16_f32 v90, v98, v93
	v_cvt_pk_bf16_f32 v91, v94, v91
	global_store_dwordx4 v[96:97], v[88:91], off
	v_max_f32_e32 v81, 0, v81
	v_max_f32_e32 v82, 0, v82
	v_mul_f32_e32 v88, v80, v80
	s_nop 0
	v_max_f32_e32 v80, 0, v85
	v_mul_f32_e32 v85, v81, v81
	v_max_f32_e32 v81, v86, v86
	v_mul_f32_e32 v86, v82, v82
	v_max_f32_e32 v84, 0, v84
	v_mul_f32_e32 v80, v80, v80
	v_max_f32_e32 v81, 0, v81
	v_max_f32_e32 v82, 0, v87
	v_max_f32_e32 v83, 0, v83
	v_mul_f32_e32 v84, v84, v84
	v_mul_f32_e32 v81, v81, v81
	v_mul_f32_e32 v82, v82, v82
	v_mul_f32_e32 v83, v83, v83
	v_cvt_pk_bf16_f32 v80, v84, v80
	v_cvt_pk_bf16_f32 v81, v81, v82
	v_cvt_pk_bf16_f32 v82, v88, v85
	v_cvt_pk_bf16_f32 v83, v86, v83
	global_store_dwordx4 v[96:97], v[80:83], off offset:256
	v_max_f32_e32 v72, 0, v72
	s_nop 0
	v_or_b32_e32 v80, 48, v152
	s_nop 0
	v_ashrrev_i32_e32 v81, 31, v80
	v_mul_f32_e32 v82, v72, v72
	v_max_f32_e32 v73, 0, v73
	v_max_f32_e32 v74, 0, v74
	v_lshlrev_b64 v[80:81], 14, v[80:81]
	v_max_f32_e32 v72, 0, v77
	v_mul_f32_e32 v77, v73, v73
	v_max_f32_e32 v73, v78, v78
	v_mul_f32_e32 v78, v74, v74
	v_lshl_add_u64 v[80:81], s[8:9], 0, v[80:81]
	v_max_f32_e32 v76, 0, v76
	v_mul_f32_e32 v72, v72, v72
	v_max_f32_e32 v73, 0, v73
	v_max_f32_e32 v74, 0, v79
	v_max_f32_e32 v75, 0, v75
	v_lshl_add_u64 v[80:81], v[80:81], 0, v[156:157]
	v_mul_f32_e32 v76, v76, v76
	v_mul_f32_e32 v73, v73, v73
	v_mul_f32_e32 v74, v74, v74
	v_mul_f32_e32 v75, v75, v75
; __device__ __forceinline__ unsigned cvt_pk_bf16(float lo, float hi) { unsigned r; asm volatile("v_cvt_pk_bf16_f32 %0, %1, %2" : "=v"(r) : "v"(lo), "v"(hi)); return r; }
;     __device__ __forceinline__ void operator()(const pg8::f32x4 (&acc)[2][2][4][2], const pg8::Unit& u, int wr, int wc, int fr, int fq) const {
;     ...
;             for (int m = 0; m < 4; ++m) { bf16* rowp = O + (size_t)(row0 + ai * 128 + m * 16) * ldc + col0;
; #pragma unroll
;                 for (int bj = 0; bj < 2; ++bj) { pg8::f32x4 v0 = acc[ai][bj][m][0], v1 = acc[ai][bj][m][1];
;                     if (ACT == 1) {
; #pragma unroll
;                         for (int e = 0; e < 4; ++e) { float a = fmaxf(v0[e], 0.f), b = fmaxf(v1[e], 0.f); v0[e] = a * a; v1[e] = b * b; } }
;                     u32x4 w; w.x = pg8::cvt_pk_bf16(v0[0], v0[1]); w.y = pg8::cvt_pk_bf16(v0[2], v0[3]); w.z = pg8::cvt_pk_bf16(v1[0], v1[1]); w.w = pg8::cvt_pk_bf16(v1[2], v1[3]);
;                     *(u32x4*)(rowp + bj * 128) = w; } }
	v_cvt_pk_bf16_f32 v72, v76, v72
	v_max_f32_e32 v64, 0, v64
	v_max_f32_e32 v65, 0, v65
	v_max_f32_e32 v66, 0, v66
	v_cvt_pk_bf16_f32 v73, v73, v74
	v_cvt_pk_bf16_f32 v74, v82, v77
	v_cvt_pk_bf16_f32 v75, v78, v75
	global_store_dwordx4 v[80:81], v[72:75], off
	s_nop 0
	s_nop 0
	v_mul_f32_e32 v72, v64, v64
	v_max_f32_e32 v64, v69, v69
	v_mul_f32_e32 v69, v65, v65
	v_max_f32_e32 v65, v70, v70
	v_mul_f32_e32 v70, v66, v66
	v_max_f32_e32 v64, 0, v64
	v_max_f32_e32 v65, 0, v65
	v_max_f32_e32 v66, 0, v71
	v_max_f32_e32 v68, 0, v68
	v_mul_f32_e32 v64, v64, v64
	v_mul_f32_e32 v65, v65, v65
	v_max_f32_e32 v67, 0, v67
	v_mul_f32_e32 v66, v66, v66
	v_mul_f32_e32 v68, v68, v68
	v_mul_f32_e32 v67, v67, v67
	v_cvt_pk_bf16_f32 v64, v68, v64
	v_cvt_pk_bf16_f32 v65, v65, v66
	v_cvt_pk_bf16_f32 v66, v72, v69
	v_max_f32_e32 v56, 0, v56
	v_cvt_pk_bf16_f32 v67, v70, v67
	global_store_dwordx4 v[80:81], v[64:67], off offset:256
	s_nop 0
	v_max_f32_e32 v57, 0, v57
	v_mul_f32_e32 v66, v56, v56
	s_nop 0
	v_max_f32_e32 v58, 0, v58
	v_max_f32_e32 v60, 0, v60
	v_max_f32_e32 v56, 0, v61
	v_mul_f32_e32 v61, v57, v57
	v_max_f32_e32 v57, v62, v62
	v_mul_f32_e32 v62, v58, v58
	v_mul_f32_e32 v60, v60, v60
	v_mul_f32_e32 v56, v56, v56
	v_max_f32_e32 v57, 0, v57
	v_max_f32_e32 v58, 0, v63
	s_mov_b32 s2, 0x200000
	v_mul_f32_e32 v57, v57, v57
	v_max_f32_e32 v59, 0, v59
	v_mul_f32_e32 v58, v58, v58
	v_cvt_pk_bf16_f32 v56, v60, v56
	v_add_co_u32_e32 v60, vcc, s2, v144
	v_mul_f32_e32 v59, v59, v59
	v_cvt_pk_bf16_f32 v57, v57, v58
	v_cvt_pk_bf16_f32 v58, v66, v61
	v_addc_co_u32_e32 v61, vcc, 0, v145, vcc
	v_max_f32_e32 v48, 0, v48
	v_max_f32_e32 v49, 0, v49
	v_max_f32_e32 v50, 0, v50
	v_cvt_pk_bf16_f32 v59, v62, v59
	global_store_dwordx4 v[60:61], v[56:59], off
	s_nop 0
	s_nop 0
	v_mul_f32_e32 v56, v48, v48
	v_max_f32_e32 v48, v53, v53
	v_mul_f32_e32 v53, v49, v49
	v_max_f32_e32 v49, v54, v54
	v_mul_f32_e32 v54, v50, v50
	v_max_f32_e32 v48, 0, v48
	v_max_f32_e32 v49, 0, v49
	v_max_f32_e32 v50, 0, v55
	s_mov_b64 s[60:61], 0x200000
	v_max_f32_e32 v52, 0, v52
	v_mul_f32_e32 v48, v48, v48
	v_mul_f32_e32 v49, v49, v49
	v_max_f32_e32 v51, 0, v51
	v_mul_f32_e32 v50, v50, v50
	v_lshl_add_u64 v[64:65], v[144:145], 0, s[60:61]
	v_mul_f32_e32 v52, v52, v52
	v_mul_f32_e32 v51, v51, v51
	v_cvt_pk_bf16_f32 v48, v52, v48
	v_cvt_pk_bf16_f32 v49, v49, v50
	v_cvt_pk_bf16_f32 v50, v56, v53
	v_max_f32_e32 v40, 0, v40
	v_cvt_pk_bf16_f32 v51, v54, v51
	global_store_dwordx4 v[64:65], v[48:51], off offset:256
	s_nop 0
	v_max_f32_e32 v41, 0, v41
	v_mul_f32_e32 v50, v40, v40
	s_nop 0
	v_max_f32_e32 v42, 0, v42
	v_max_f32_e32 v44, 0, v44
	v_max_f32_e32 v40, 0, v45
	v_mul_f32_e32 v45, v41, v41
	v_max_f32_e32 v41, v46, v46
	v_mul_f32_e32 v46, v42, v42
	v_mul_f32_e32 v44, v44, v44
	v_mul_f32_e32 v40, v40, v40
	v_max_f32_e32 v41, 0, v41
	v_max_f32_e32 v42, 0, v47
	s_mov_b32 s2, 0x240000
	v_mul_f32_e32 v41, v41, v41
	v_max_f32_e32 v43, 0, v43
	v_mul_f32_e32 v42, v42, v42
	v_cvt_pk_bf16_f32 v40, v44, v40
	v_add_co_u32_e32 v44, vcc, s2, v144
	v_mul_f32_e32 v43, v43, v43
	v_cvt_pk_bf16_f32 v41, v41, v42
	v_cvt_pk_bf16_f32 v42, v50, v45
	v_addc_co_u32_e32 v45, vcc, 0, v145, vcc
	v_max_f32_e32 v32, 0, v32
	v_max_f32_e32 v33, 0, v33
	v_max_f32_e32 v34, 0, v34
	v_cvt_pk_bf16_f32 v43, v46, v43
	global_store_dwordx4 v[44:45], v[40:43], off
	s_nop 0
	s_nop 0
	v_mul_f32_e32 v40, v32, v32
	v_max_f32_e32 v32, v37, v37
	v_mul_f32_e32 v37, v33, v33
	v_max_f32_e32 v33, v38, v38
	v_mul_f32_e32 v38, v34, v34
	v_max_f32_e32 v32, 0, v32
	v_max_f32_e32 v33, 0, v33
	v_max_f32_e32 v34, 0, v39
	s_mov_b64 s[60:61], 0x240000
	v_max_f32_e32 v36, 0, v36
; __device__ __forceinline__ unsigned cvt_pk_bf16(float lo, float hi) { unsigned r; asm volatile("v_cvt_pk_bf16_f32 %0, %1, %2" : "=v"(r) : "v"(lo), "v"(hi)); return r; }
;     __device__ __forceinline__ void operator()(const pg8::f32x4 (&acc)[2][2][4][2], const pg8::Unit& u, int wr, int wc, int fr, int fq) const {
;     ...
;             for (int m = 0; m < 4; ++m) { bf16* rowp = O + (size_t)(row0 + ai * 128 + m * 16) * ldc + col0;
; #pragma unroll
;                 for (int bj = 0; bj < 2; ++bj) { pg8::f32x4 v0 = acc[ai][bj][m][0], v1 = acc[ai][bj][m][1];
;                     if (ACT == 1) {
; #pragma unroll
;                         for (int e = 0; e < 4; ++e) { float a = fmaxf(v0[e], 0.f), b = fmaxf(v1[e], 0.f); v0[e] = a * a; v1[e] = b * b; } }
;                     u32x4 w; w.x = pg8::cvt_pk_bf16(v0[0], v0[1]); w.y = pg8::cvt_pk_bf16(v0[2], v0[3]); w.z = pg8::cvt_pk_bf16(v1[0], v1[1]); w.w = pg8::cvt_pk_bf16(v1[2], v1[3]);
;                     *(u32x4*)(rowp + bj * 128) = w; } }
	v_mul_f32_e32 v32, v32, v32
	v_mul_f32_e32 v33, v33, v33
	v_max_f32_e32 v35, 0, v35
	v_mul_f32_e32 v34, v34, v34
	v_lshl_add_u64 v[48:49], v[144:145], 0, s[60:61]
	v_mul_f32_e32 v36, v36, v36
	v_mul_f32_e32 v35, v35, v35
	v_cvt_pk_bf16_f32 v32, v36, v32
	v_cvt_pk_bf16_f32 v33, v33, v34
	v_cvt_pk_bf16_f32 v34, v40, v37
	v_max_f32_e32 v24, 0, v24
	v_cvt_pk_bf16_f32 v35, v38, v35
	global_store_dwordx4 v[48:49], v[32:35], off offset:256
	s_nop 0
	v_max_f32_e32 v25, 0, v25
	v_mul_f32_e32 v34, v24, v24
	s_nop 0
	v_max_f32_e32 v26, 0, v26
	v_max_f32_e32 v28, 0, v28
	v_max_f32_e32 v24, 0, v29
	v_mul_f32_e32 v29, v25, v25
	v_max_f32_e32 v25, v30, v30
	v_mul_f32_e32 v30, v26, v26
	v_mul_f32_e32 v28, v28, v28
	v_mul_f32_e32 v24, v24, v24
	v_max_f32_e32 v25, 0, v25
	v_max_f32_e32 v26, 0, v31
	s_mov_b32 s2, 0x280000
	v_mul_f32_e32 v25, v25, v25
	v_max_f32_e32 v27, 0, v27
	v_mul_f32_e32 v26, v26, v26
	v_cvt_pk_bf16_f32 v24, v28, v24
	v_add_co_u32_e32 v28, vcc, s2, v144
	v_mul_f32_e32 v27, v27, v27
	v_cvt_pk_bf16_f32 v25, v25, v26
	v_cvt_pk_bf16_f32 v26, v34, v29
	v_addc_co_u32_e32 v29, vcc, 0, v145, vcc
	v_max_f32_e32 v16, 0, v16
	v_max_f32_e32 v17, 0, v17
	v_max_f32_e32 v18, 0, v18
	v_cvt_pk_bf16_f32 v27, v30, v27
	global_store_dwordx4 v[28:29], v[24:27], off
	s_nop 0
	s_nop 0
	v_mul_f32_e32 v24, v16, v16
	v_max_f32_e32 v16, v21, v21
	v_mul_f32_e32 v21, v17, v17
	v_max_f32_e32 v17, v22, v22
	v_mul_f32_e32 v22, v18, v18
	v_max_f32_e32 v16, 0, v16
	v_max_f32_e32 v17, 0, v17
	v_max_f32_e32 v18, 0, v23
	s_mov_b64 s[60:61], 0x280000
	v_max_f32_e32 v20, 0, v20
	v_mul_f32_e32 v16, v16, v16
	v_mul_f32_e32 v17, v17, v17
	v_max_f32_e32 v19, 0, v19
	v_mul_f32_e32 v18, v18, v18
	v_lshl_add_u64 v[32:33], v[144:145], 0, s[60:61]
	v_mul_f32_e32 v20, v20, v20
	v_mul_f32_e32 v19, v19, v19
	v_cvt_pk_bf16_f32 v16, v20, v16
	v_cvt_pk_bf16_f32 v17, v17, v18
	v_cvt_pk_bf16_f32 v18, v24, v21
	v_max_f32_e32 v8, 0, v8
	v_cvt_pk_bf16_f32 v19, v22, v19
	global_store_dwordx4 v[32:33], v[16:19], off offset:256
	s_nop 0
	v_max_f32_e32 v9, 0, v9
	v_mul_f32_e32 v18, v8, v8
	s_nop 0
	v_max_f32_e32 v10, 0, v10
	v_max_f32_e32 v12, 0, v12
	v_max_f32_e32 v8, 0, v13
	v_mul_f32_e32 v13, v9, v9
	v_max_f32_e32 v9, v14, v14
	v_mul_f32_e32 v14, v10, v10
	v_mul_f32_e32 v12, v12, v12
	v_mul_f32_e32 v8, v8, v8
	v_max_f32_e32 v9, 0, v9
	v_max_f32_e32 v10, 0, v15
	s_mov_b32 s2, 0x2c0000
	v_mul_f32_e32 v9, v9, v9
	v_max_f32_e32 v11, 0, v11
	v_mul_f32_e32 v10, v10, v10
	v_cvt_pk_bf16_f32 v8, v12, v8
	v_add_co_u32_e32 v12, vcc, s2, v144
	v_mul_f32_e32 v11, v11, v11
	v_cvt_pk_bf16_f32 v9, v9, v10
	v_cvt_pk_bf16_f32 v10, v18, v13
	v_addc_co_u32_e32 v13, vcc, 0, v145, vcc
	v_max_f32_e32 v0, 0, v0
	v_max_f32_e32 v1, 0, v1
	v_max_f32_e32 v2, 0, v2
	v_cvt_pk_bf16_f32 v11, v14, v11
	global_store_dwordx4 v[12:13], v[8:11], off
	s_nop 0
	s_mov_b64 s[60:61], 0x2c0000
	v_mul_f32_e32 v8, v0, v0
	v_max_f32_e32 v0, v5, v5
	v_mul_f32_e32 v5, v1, v1
	v_max_f32_e32 v1, v6, v6
	v_mul_f32_e32 v6, v2, v2
	v_max_f32_e32 v0, 0, v0
	v_max_f32_e32 v1, 0, v1
	v_max_f32_e32 v2, 0, v7
	v_max_f32_e32 v3, 0, v3
	v_lshl_add_u64 v[16:17], v[144:145], 0, s[60:61]
	v_max_f32_e32 v4, 0, v4
	v_mul_f32_e32 v0, v0, v0
	v_mul_f32_e32 v1, v1, v1
	v_mul_f32_e32 v2, v2, v2
	v_mul_f32_e32 v3, v3, v3
	s_andn2_b64 vcc, exec, s[0:1]
	s_mov_b64 s[0:1], -1
	v_mul_f32_e32 v4, v4, v4
	v_cvt_pk_bf16_f32 v0, v4, v0
	v_cvt_pk_bf16_f32 v1, v1, v2
	v_cvt_pk_bf16_f32 v2, v8, v5
	v_cvt_pk_bf16_f32 v3, v6, v3
	global_store_dwordx4 v[16:17], v[0:3], off offset:256
	s_cbranch_vccnz .LBB0_864
	s_andn2_b64 vcc, exec, s[4:5]
	s_cbranch_vccnz .LBB0_863
	s_barrier
	s_branch .LBB0_863

; __device__ __forceinline__ unsigned cvt_pk_bf16(float lo, float hi) { unsigned r; asm volatile("v_cvt_pk_bf16_f32 %0, %1, %2" : "=v"(r) : "v"(lo), "v"(hi)); return r; }
;     __device__ __forceinline__ void operator()(const pg8::f32x4 (&acc)[2][2][4][2], const pg8::Unit& u, int wr, int wc, int fr, int fq) const {
;         const int row0 = u.pm * 256 + wr * 64 + fr, col0 = u.pn * 256 + wc * 32 + 8 * fq;
; #pragma unroll
;         for (int ai = 0; ai < 2; ++ai)
; #pragma unroll
;             for (int m = 0; m < 4; ++m) { bf16* rowp = O + (size_t)(row0 + ai * 128 + m * 16) * ldc + col0;
; #pragma unroll
;                 for (int bj = 0; bj < 2; ++bj) { pg8::f32x4 v0 = acc[ai][bj][m][0], v1 = acc[ai][bj][m][1];
;                     if (ACT == 1) {
; #pragma unroll
;                         for (int e = 0; e < 4; ++e) { float a = fmaxf(v0[e], 0.f), b = fmaxf(v1[e], 0.f); v0[e] = a * a; v1[e] = b * b; } }
;                     u32x4 w; w.x = pg8::cvt_pk_bf16(v0[0], v0[1]); w.y = pg8::cvt_pk_bf16(v0[2], v0[3]); w.z = pg8::cvt_pk_bf16(v1[0], v1[1]); w.w = pg8::cvt_pk_bf16(v1[2], v1[3]);
;                     *(u32x4*)(rowp + bj * 128) = w; } }
.LBB0_1911:
	v_lshl_add_u32 v152, s34, 8, v146
	v_ashrrev_i32_e32 v153, 31, v152
	v_max_f32_e32 v120, 0, v120
	v_lshl_or_b32 v144, s56, 8, v148
	v_lshlrev_b64 v[154:155], 14, v[152:153]
	v_mul_f32_e32 v153, v120, v120
	v_max_f32_e32 v121, 0, v121
	v_max_f32_e32 v122, 0, v122
	v_ashrrev_i32_e32 v145, 31, v144
	v_max_f32_e32 v120, 0, v125
	v_mul_f32_e32 v125, v121, v121
	v_max_f32_e32 v121, v126, v126
	v_mul_f32_e32 v126, v122, v122
	v_lshl_add_u64 v[154:155], s[8:9], 0, v[154:155]
	v_lshlrev_b64 v[156:157], 1, v[144:145]
	v_max_f32_e32 v124, 0, v124
	v_mul_f32_e32 v120, v120, v120
	v_max_f32_e32 v121, 0, v121
	v_max_f32_e32 v122, 0, v127
	v_max_f32_e32 v123, 0, v123
	v_lshl_add_u64 v[144:145], v[154:155], 0, v[156:157]
	v_mul_f32_e32 v124, v124, v124
	v_mul_f32_e32 v121, v121, v121
	v_mul_f32_e32 v122, v122, v122
	v_mul_f32_e32 v123, v123, v123
	v_cvt_pk_bf16_f32 v120, v124, v120
	v_max_f32_e32 v112, 0, v112
	v_cvt_pk_bf16_f32 v121, v121, v122
	v_cvt_pk_bf16_f32 v122, v153, v125
	v_cvt_pk_bf16_f32 v123, v126, v123
	global_store_dwordx4 v[144:145], v[120:123], off
	v_max_f32_e32 v113, 0, v113
	v_max_f32_e32 v114, 0, v114
	v_mul_f32_e32 v120, v112, v112
	s_nop 0
	v_max_f32_e32 v112, 0, v117
	v_mul_f32_e32 v117, v113, v113
	v_max_f32_e32 v113, v118, v118
	v_mul_f32_e32 v118, v114, v114
	v_max_f32_e32 v116, 0, v116
	v_mul_f32_e32 v112, v112, v112
	v_max_f32_e32 v113, 0, v113
	v_max_f32_e32 v114, 0, v119
	v_max_f32_e32 v115, 0, v115
	v_mul_f32_e32 v116, v116, v116
	v_mul_f32_e32 v113, v113, v113
	v_mul_f32_e32 v114, v114, v114
	v_mul_f32_e32 v115, v115, v115
	v_cvt_pk_bf16_f32 v112, v116, v112
	v_cvt_pk_bf16_f32 v113, v113, v114
	v_cvt_pk_bf16_f32 v114, v120, v117
	v_cvt_pk_bf16_f32 v115, v118, v115
	global_store_dwordx4 v[144:145], v[112:115], off offset:256
	v_max_f32_e32 v104, 0, v104
	s_nop 0
	v_or_b32_e32 v112, 16, v152
	s_nop 0
	v_ashrrev_i32_e32 v113, 31, v112
	v_mul_f32_e32 v114, v104, v104
	v_max_f32_e32 v105, 0, v105
	v_max_f32_e32 v106, 0, v106
	v_lshlrev_b64 v[112:113], 14, v[112:113]
	v_max_f32_e32 v104, 0, v109
	v_mul_f32_e32 v109, v105, v105
	v_max_f32_e32 v105, v110, v110
	v_mul_f32_e32 v110, v106, v106
	v_lshl_add_u64 v[112:113], s[8:9], 0, v[112:113]
	v_max_f32_e32 v108, 0, v108
	v_mul_f32_e32 v104, v104, v104
	v_max_f32_e32 v105, 0, v105
	v_max_f32_e32 v106, 0, v111
	v_max_f32_e32 v107, 0, v107
	v_lshl_add_u64 v[112:113], v[112:113], 0, v[156:157]
	v_mul_f32_e32 v108, v108, v108
	v_mul_f32_e32 v105, v105, v105
	v_mul_f32_e32 v106, v106, v106
	v_mul_f32_e32 v107, v107, v107
	v_cvt_pk_bf16_f32 v104, v108, v104
	v_max_f32_e32 v96, 0, v96
	v_cvt_pk_bf16_f32 v105, v105, v106
	v_cvt_pk_bf16_f32 v106, v114, v109
	v_cvt_pk_bf16_f32 v107, v110, v107
	global_store_dwordx4 v[112:113], v[104:107], off
	v_max_f32_e32 v97, 0, v97
	v_max_f32_e32 v98, 0, v98
	v_mul_f32_e32 v104, v96, v96
	s_nop 0
	v_max_f32_e32 v96, 0, v101
	v_mul_f32_e32 v101, v97, v97
	v_max_f32_e32 v97, v102, v102
	v_mul_f32_e32 v102, v98, v98
	v_max_f32_e32 v100, 0, v100
	v_mul_f32_e32 v96, v96, v96
	v_max_f32_e32 v97, 0, v97
	v_max_f32_e32 v98, 0, v103
	v_max_f32_e32 v99, 0, v99
	v_mul_f32_e32 v100, v100, v100
	v_mul_f32_e32 v97, v97, v97
	v_mul_f32_e32 v98, v98, v98
	v_mul_f32_e32 v99, v99, v99
	v_cvt_pk_bf16_f32 v96, v100, v96
	v_cvt_pk_bf16_f32 v97, v97, v98
	v_cvt_pk_bf16_f32 v98, v104, v101
	v_cvt_pk_bf16_f32 v99, v102, v99
	global_store_dwordx4 v[112:113], v[96:99], off offset:256
	v_max_f32_e32 v88, 0, v88
	s_nop 0
	v_or_b32_e32 v96, 32, v152
	s_nop 0
	v_ashrrev_i32_e32 v97, 31, v96
	v_mul_f32_e32 v98, v88, v88
	v_max_f32_e32 v89, 0, v89
	v_max_f32_e32 v90, 0, v90
	v_lshlrev_b64 v[96:97], 14, v[96:97]
	v_max_f32_e32 v88, 0, v93
	v_mul_f32_e32 v93, v89, v89
	v_max_f32_e32 v89, v94, v94
	v_mul_f32_e32 v94, v90, v90
	v_lshl_add_u64 v[96:97], s[8:9], 0, v[96:97]
	v_max_f32_e32 v92, 0, v92
	v_mul_f32_e32 v88, v88, v88
	v_max_f32_e32 v89, 0, v89
	v_max_f32_e32 v90, 0, v95
	v_max_f32_e32 v91, 0, v91
	v_lshl_add_u64 v[96:97], v[96:97], 0, v[156:157]
	v_mul_f32_e32 v92, v92, v92
	v_mul_f32_e32 v89, v89, v89
	v_mul_f32_e32 v90, v90, v90
	v_mul_f32_e32 v91, v91, v91
	v_cvt_pk_bf16_f32 v88, v92, v88
	v_max_f32_e32 v80, 0, v80
	v_cvt_pk_bf16_f32 v89, v89, v90
	v_cvt_pk_bf16_f32 v90, v98, v93
	v_cvt_pk_bf16_f32 v91, v94, v91
	global_store_dwordx4 v[96:97], v[88:91], off
	v_max_f32_e32 v81, 0, v81
	v_max_f32_e32 v82, 0, v82
	v_mul_f32_e32 v88, v80, v80
	s_nop 0
	v_max_f32_e32 v80, 0, v85
	v_mul_f32_e32 v85, v81, v81
	v_max_f32_e32 v81, v86, v86
	v_mul_f32_e32 v86, v82, v82
	v_max_f32_e32 v84, 0, v84
	v_mul_f32_e32 v80, v80, v80
	v_max_f32_e32 v81, 0, v81
	v_max_f32_e32 v82, 0, v87
	v_max_f32_e32 v83, 0, v83
	v_mul_f32_e32 v84, v84, v84
	v_mul_f32_e32 v81, v81, v81
	v_mul_f32_e32 v82, v82, v82
	v_mul_f32_e32 v83, v83, v83
	v_cvt_pk_bf16_f32 v80, v84, v80
	v_cvt_pk_bf16_f32 v81, v81, v82
	v_cvt_pk_bf16_f32 v82, v88, v85
	v_cvt_pk_bf16_f32 v83, v86, v83
	global_store_dwordx4 v[96:97], v[80:83], off offset:256
	v_max_f32_e32 v72, 0, v72
	s_nop 0
	v_or_b32_e32 v80, 48, v152
	s_nop 0
	v_ashrrev_i32_e32 v81, 31, v80
	v_mul_f32_e32 v82, v72, v72
	v_max_f32_e32 v73, 0, v73
	v_max_f32_e32 v74, 0, v74
	v_lshlrev_b64 v[80:81], 14, v[80:81]
	v_max_f32_e32 v72, 0, v77
	v_mul_f32_e32 v77, v73, v73
	v_max_f32_e32 v73, v78, v78
	v_mul_f32_e32 v78, v74, v74
	v_lshl_add_u64 v[80:81], s[8:9], 0, v[80:81]
	v_max_f32_e32 v76, 0, v76
	v_mul_f32_e32 v72, v72, v72
	v_max_f32_e32 v73, 0, v73
	v_max_f32_e32 v74, 0, v79
	v_max_f32_e32 v75, 0, v75
	v_lshl_add_u64 v[80:81], v[80:81], 0, v[156:157]
	v_mul_f32_e32 v76, v76, v76
	v_mul_f32_e32 v73, v73, v73
	v_mul_f32_e32 v74, v74, v74
	v_mul_f32_e32 v75, v75, v75
; __device__ __forceinline__ unsigned cvt_pk_bf16(float lo, float hi) { unsigned r; asm volatile("v_cvt_pk_bf16_f32 %0, %1, %2" : "=v"(r) : "v"(lo), "v"(hi)); return r; }
;     __device__ __forceinline__ void operator()(const pg8::f32x4 (&acc)[2][2][4][2], const pg8::Unit& u, int wr, int wc, int fr, int fq) const {
;     ...
;             for (int m = 0; m < 4; ++m) { bf16* rowp = O + (size_t)(row0 + ai * 128 + m * 16) * ldc + col0;
; #pragma unroll
;                 for (int bj = 0; bj < 2; ++bj) { pg8::f32x4 v0 = acc[ai][bj][m][0], v1 = acc[ai][bj][m][1];
;                     if (ACT == 1) {
; #pragma unroll
;                         for (int e = 0; e < 4; ++e) { float a = fmaxf(v0[e], 0.f), b = fmaxf(v1[e], 0.f); v0[e] = a * a; v1[e] = b * b; } }
;                     u32x4 w; w.x = pg8::cvt_pk_bf16(v0[0], v0[1]); w.y = pg8::cvt_pk_bf16(v0[2], v0[3]); w.z = pg8::cvt_pk_bf16(v1[0], v1[1]); w.w = pg8::cvt_pk_bf16(v1[2], v1[3]);
;                     *(u32x4*)(rowp + bj * 128) = w; } }
	v_cvt_pk_bf16_f32 v72, v76, v72
	v_max_f32_e32 v64, 0, v64
	v_max_f32_e32 v65, 0, v65
	v_max_f32_e32 v66, 0, v66
	v_cvt_pk_bf16_f32 v73, v73, v74
	v_cvt_pk_bf16_f32 v74, v82, v77
	v_cvt_pk_bf16_f32 v75, v78, v75
	global_store_dwordx4 v[80:81], v[72:75], off
	s_nop 0
	s_nop 0
	v_mul_f32_e32 v72, v64, v64
	v_max_f32_e32 v64, v69, v69
	v_mul_f32_e32 v69, v65, v65
	v_max_f32_e32 v65, v70, v70
	v_mul_f32_e32 v70, v66, v66
	v_max_f32_e32 v64, 0, v64
	v_max_f32_e32 v65, 0, v65
	v_max_f32_e32 v66, 0, v71
	v_max_f32_e32 v68, 0, v68
	v_mul_f32_e32 v64, v64, v64
	v_mul_f32_e32 v65, v65, v65
	v_max_f32_e32 v67, 0, v67
	v_mul_f32_e32 v66, v66, v66
	v_mul_f32_e32 v68, v68, v68
	v_mul_f32_e32 v67, v67, v67
	v_cvt_pk_bf16_f32 v64, v68, v64
	v_cvt_pk_bf16_f32 v65, v65, v66
	v_cvt_pk_bf16_f32 v66, v72, v69
	v_max_f32_e32 v56, 0, v56
	v_cvt_pk_bf16_f32 v67, v70, v67
	global_store_dwordx4 v[80:81], v[64:67], off offset:256
	s_nop 0
	v_max_f32_e32 v57, 0, v57
	v_mul_f32_e32 v66, v56, v56
	s_nop 0
	v_max_f32_e32 v58, 0, v58
	v_max_f32_e32 v60, 0, v60
	v_max_f32_e32 v56, 0, v61
	v_mul_f32_e32 v61, v57, v57
	v_max_f32_e32 v57, v62, v62
	v_mul_f32_e32 v62, v58, v58
	v_mul_f32_e32 v60, v60, v60
	v_mul_f32_e32 v56, v56, v56
	v_max_f32_e32 v57, 0, v57
	v_max_f32_e32 v58, 0, v63
	v_mul_f32_e32 v57, v57, v57
	v_max_f32_e32 v59, 0, v59
	v_mul_f32_e32 v58, v58, v58
	v_cvt_pk_bf16_f32 v56, v60, v56
	v_add_co_u32_e32 v60, vcc, s52, v144
	v_mul_f32_e32 v59, v59, v59
	v_cvt_pk_bf16_f32 v57, v57, v58
	v_cvt_pk_bf16_f32 v58, v66, v61
	v_addc_co_u32_e32 v61, vcc, 0, v145, vcc
	v_max_f32_e32 v48, 0, v48
	v_max_f32_e32 v49, 0, v49
	v_max_f32_e32 v50, 0, v50
	v_cvt_pk_bf16_f32 v59, v62, v59
	global_store_dwordx4 v[60:61], v[56:59], off
	s_nop 0
	s_nop 0
	v_mul_f32_e32 v56, v48, v48
	v_max_f32_e32 v48, v53, v53
	v_mul_f32_e32 v53, v49, v49
	v_max_f32_e32 v49, v54, v54
	v_mul_f32_e32 v54, v50, v50
	v_max_f32_e32 v48, 0, v48
	v_max_f32_e32 v49, 0, v49
	v_max_f32_e32 v50, 0, v55
	v_max_f32_e32 v52, 0, v52
	v_mul_f32_e32 v48, v48, v48
	v_mul_f32_e32 v49, v49, v49
	v_max_f32_e32 v51, 0, v51
	v_mul_f32_e32 v50, v50, v50
	v_lshl_add_u64 v[64:65], v[144:145], 0, s[14:15]
	v_mul_f32_e32 v52, v52, v52
	v_mul_f32_e32 v51, v51, v51
	v_cvt_pk_bf16_f32 v48, v52, v48
	v_cvt_pk_bf16_f32 v49, v49, v50
	v_cvt_pk_bf16_f32 v50, v56, v53
	v_max_f32_e32 v40, 0, v40
	v_cvt_pk_bf16_f32 v51, v54, v51
	global_store_dwordx4 v[64:65], v[48:51], off offset:256
	s_nop 0
	v_max_f32_e32 v41, 0, v41
	v_mul_f32_e32 v50, v40, v40
	s_nop 0
	v_max_f32_e32 v42, 0, v42
	v_max_f32_e32 v44, 0, v44
	v_max_f32_e32 v40, 0, v45
	v_mul_f32_e32 v45, v41, v41
	v_max_f32_e32 v41, v46, v46
	v_mul_f32_e32 v46, v42, v42
	v_mul_f32_e32 v44, v44, v44
	v_mul_f32_e32 v40, v40, v40
	v_max_f32_e32 v41, 0, v41
	v_max_f32_e32 v42, 0, v47
	v_mul_f32_e32 v41, v41, v41
	v_max_f32_e32 v43, 0, v43
	v_mul_f32_e32 v42, v42, v42
	v_cvt_pk_bf16_f32 v40, v44, v40
	v_add_co_u32_e32 v44, vcc, s53, v144
	v_mul_f32_e32 v43, v43, v43
	v_cvt_pk_bf16_f32 v41, v41, v42
	v_cvt_pk_bf16_f32 v42, v50, v45
	v_addc_co_u32_e32 v45, vcc, 0, v145, vcc
	v_max_f32_e32 v32, 0, v32
	v_max_f32_e32 v33, 0, v33
	v_max_f32_e32 v34, 0, v34
	v_cvt_pk_bf16_f32 v43, v46, v43
	global_store_dwordx4 v[44:45], v[40:43], off
	s_nop 0
	s_nop 0
	v_mul_f32_e32 v40, v32, v32
	v_max_f32_e32 v32, v37, v37
	v_mul_f32_e32 v37, v33, v33
	v_max_f32_e32 v33, v38, v38
	v_mul_f32_e32 v38, v34, v34
	v_max_f32_e32 v32, 0, v32
	v_max_f32_e32 v33, 0, v33
	v_max_f32_e32 v34, 0, v39
	v_max_f32_e32 v36, 0, v36
	v_mul_f32_e32 v32, v32, v32
	v_mul_f32_e32 v33, v33, v33
	v_max_f32_e32 v35, 0, v35
	v_mul_f32_e32 v34, v34, v34
	v_lshl_add_u64 v[48:49], v[144:145], 0, s[16:17]
	v_mul_f32_e32 v36, v36, v36
	v_mul_f32_e32 v35, v35, v35
	v_cvt_pk_bf16_f32 v32, v36, v32
	v_cvt_pk_bf16_f32 v33, v33, v34
	v_cvt_pk_bf16_f32 v34, v40, v37
	v_max_f32_e32 v24, 0, v24
	v_cvt_pk_bf16_f32 v35, v38, v35
	global_store_dwordx4 v[48:49], v[32:35], off offset:256
	s_nop 0
	v_max_f32_e32 v25, 0, v25
	v_mul_f32_e32 v34, v24, v24
	s_nop 0
	v_max_f32_e32 v26, 0, v26
	v_max_f32_e32 v28, 0, v28
	v_max_f32_e32 v24, 0, v29
	v_mul_f32_e32 v29, v25, v25
	v_max_f32_e32 v25, v30, v30
	v_mul_f32_e32 v30, v26, v26
	v_mul_f32_e32 v28, v28, v28
	v_mul_f32_e32 v24, v24, v24
	v_max_f32_e32 v25, 0, v25
	v_max_f32_e32 v26, 0, v31
	v_mul_f32_e32 v25, v25, v25
	v_max_f32_e32 v27, 0, v27
	v_mul_f32_e32 v26, v26, v26
	v_cvt_pk_bf16_f32 v24, v28, v24
	v_add_co_u32_e32 v28, vcc, s54, v144
	v_mul_f32_e32 v27, v27, v27
	v_cvt_pk_bf16_f32 v25, v25, v26
	v_cvt_pk_bf16_f32 v26, v34, v29
	v_addc_co_u32_e32 v29, vcc, 0, v145, vcc
	v_max_f32_e32 v16, 0, v16
	v_max_f32_e32 v17, 0, v17
	v_max_f32_e32 v18, 0, v18
	v_cvt_pk_bf16_f32 v27, v30, v27
	global_store_dwordx4 v[28:29], v[24:27], off
	s_nop 0
	s_nop 0
	v_mul_f32_e32 v24, v16, v16
	v_max_f32_e32 v16, v21, v21
	v_mul_f32_e32 v21, v17, v17
	v_max_f32_e32 v17, v22, v22
	v_mul_f32_e32 v22, v18, v18
	v_max_f32_e32 v16, 0, v16
	v_max_f32_e32 v17, 0, v17
	v_max_f32_e32 v18, 0, v23
	v_max_f32_e32 v20, 0, v20
	v_mul_f32_e32 v16, v16, v16
	v_mul_f32_e32 v17, v17, v17
	v_max_f32_e32 v19, 0, v19
	v_mul_f32_e32 v18, v18, v18
	v_lshl_add_u64 v[32:33], v[144:145], 0, s[18:19]
	v_mul_f32_e32 v20, v20, v20
	v_mul_f32_e32 v19, v19, v19
	v_cvt_pk_bf16_f32 v16, v20, v16
	v_cvt_pk_bf16_f32 v17, v17, v18
	v_cvt_pk_bf16_f32 v18, v24, v21
	v_max_f32_e32 v8, 0, v8
	v_cvt_pk_bf16_f32 v19, v22, v19
	global_store_dwordx4 v[32:33], v[16:19], off offset:256
	s_nop 0
	v_max_f32_e32 v9, 0, v9
	v_mul_f32_e32 v18, v8, v8
	s_nop 0
	v_max_f32_e32 v10, 0, v10
	v_max_f32_e32 v12, 0, v12
	v_max_f32_e32 v8, 0, v13
	v_mul_f32_e32 v13, v9, v9
	v_max_f32_e32 v9, v14, v14
	v_mul_f32_e32 v14, v10, v10
	v_mul_f32_e32 v12, v12, v12
	v_mul_f32_e32 v8, v8, v8
	v_max_f32_e32 v9, 0, v9
	v_max_f32_e32 v10, 0, v15
	v_mul_f32_e32 v9, v9, v9
	v_max_f32_e32 v11, 0, v11
	v_mul_f32_e32 v10, v10, v10
	v_cvt_pk_bf16_f32 v8, v12, v8
	v_add_co_u32_e32 v12, vcc, s55, v144
	v_mul_f32_e32 v11, v11, v11
	v_cvt_pk_bf16_f32 v9, v9, v10
	v_cvt_pk_bf16_f32 v10, v18, v13
	v_addc_co_u32_e32 v13, vcc, 0, v145, vcc
	v_max_f32_e32 v0, 0, v0
	v_max_f32_e32 v1, 0, v1
	v_max_f32_e32 v2, 0, v2
	v_cvt_pk_bf16_f32 v11, v14, v11
	global_store_dwordx4 v[12:13], v[8:11], off
	s_nop 0
	s_nop 0
	v_mul_f32_e32 v8, v0, v0
	v_max_f32_e32 v0, v5, v5
	v_mul_f32_e32 v5, v1, v1
	v_max_f32_e32 v1, v6, v6
	v_mul_f32_e32 v6, v2, v2
	v_max_f32_e32 v0, 0, v0
	v_max_f32_e32 v1, 0, v1
	v_max_f32_e32 v2, 0, v7
	v_max_f32_e32 v3, 0, v3
	v_lshl_add_u64 v[16:17], v[144:145], 0, s[20:21]
	v_max_f32_e32 v4, 0, v4
	v_mul_f32_e32 v0, v0, v0
	v_mul_f32_e32 v1, v1, v1
	v_mul_f32_e32 v2, v2, v2
	v_mul_f32_e32 v3, v3, v3
	s_andn2_b64 vcc, exec, s[0:1]
	s_mov_b64 s[0:1], -1
	v_mul_f32_e32 v4, v4, v4
	v_cvt_pk_bf16_f32 v0, v4, v0
	v_cvt_pk_bf16_f32 v1, v1, v2
	v_cvt_pk_bf16_f32 v2, v8, v5
	v_cvt_pk_bf16_f32 v3, v6, v3
	global_store_dwordx4 v[16:17], v[0:3], off offset:256
	s_cbranch_vccnz .LBB0_1900
	s_andn2_b64 vcc, exec, s[4:5]
	s_cbranch_vccnz .LBB0_1899
	s_barrier
	s_branch .LBB0_1899
